# cache-aware tile order: both ff2 phases start with the row panels ff1 wrote last (phase 8: panel^8; phase 16: round permutation 1,3,0,2)
# speedup vs baseline: 1.0154x; 1.0012x over previous
.LBB0_368:
	s_lshl_b32 s20, s85, 3
	v_cvt_f32_u32_e32 v0, s20
	s_sub_i32 s29, 0, s20
	s_ashr_i32 s6, s6, 3
	s_add_i32 s6, s27, s6
	v_rcp_iflag_f32_e32 v0, v0
	s_abs_i32 s27, s6
	s_ashr_i32 s26, s6, 31
	v_mul_f32_e32 v0, 0x4f7ffffe, v0
	v_cvt_u32_f32_e32 v0, v0
	s_nop 0
	v_readfirstlane_b32 s31, v0
	s_mul_i32 s29, s29, s31
	s_mul_hi_u32 s29, s31, s29
	s_add_i32 s31, s31, s29
	s_mul_hi_u32 s29, s27, s31
	s_mul_i32 s31, s29, s20
	s_sub_i32 s27, s27, s31
	s_add_i32 s31, s29, 1
	s_sub_i32 s38, s27, s20
	s_cmp_ge_u32 s27, s20
	s_cselect_b32 s29, s31, s29
	s_cselect_b32 s27, s38, s27
	s_add_i32 s31, s29, 1
	s_cmp_ge_u32 s27, s20
	s_cselect_b32 s27, s31, s29
	s_xor_b32 s27, s27, s26
	s_sub_i32 s26, s27, s26
	s_lshl_b32 s27, s26, 3
	s_sub_i32 s29, s92, s27
	s_min_i32 s29, s29, 8
	s_abs_i32 s31, s29
	v_cvt_f32_u32_e32 v0, s31
	s_sub_i32 s38, 0, s31
	s_mul_i32 s26, s26, s20
	s_sub_i32 s20, s6, s26
	v_rcp_iflag_f32_e32 v0, v0
	s_abs_i32 s26, s20
	s_xor_b32 s6, s20, s29
	s_ashr_i32 s6, s6, 31
	v_mul_f32_e32 v0, 0x4f7ffffe, v0
	v_cvt_u32_f32_e32 v0, v0
	s_nop 0
	v_readfirstlane_b32 s39, v0
	s_mul_i32 s38, s38, s39
	s_mul_hi_u32 s38, s39, s38
	s_add_i32 s39, s39, s38
	s_mul_hi_u32 s38, s26, s39
	v_cvt_f32_ubyte0_e32 v0, s88
	s_mul_i32 s39, s38, s31
	v_rcp_iflag_f32_e32 v0, v0
	s_sub_i32 s26, s26, s39
	s_add_i32 s39, s38, 1
	s_sub_i32 s42, s26, s31
	s_cmp_ge_u32 s26, s31
	s_cselect_b32 s38, s39, s38
	v_mul_f32_e32 v0, 0x4f7ffffe, v0
	s_cselect_b32 s26, s42, s26
	s_add_i32 s39, s38, 1
	v_cvt_u32_f32_e32 v0, v0
	s_cmp_ge_u32 s26, s31
	s_cselect_b32 s26, s39, s38
	s_xor_b32 s26, s26, s6
	s_sub_i32 s6, s26, s6
	v_readfirstlane_b32 s31, v0
	v_cvt_f32_u32_e32 v0, s85
	s_mul_i32 s26, s6, s29
	s_sub_i32 s29, 0, s88
	s_mul_i32 s29, s29, s31
	s_sub_i32 s20, s20, s26
	s_mul_hi_u32 s29, s31, s29
	s_add_i32 s20, s20, s27
	s_abs_i32 s27, s2
	s_add_i32 s31, s31, s29
	v_rcp_iflag_f32_e32 v0, v0
	s_mul_hi_u32 s29, s27, s31
	s_mul_i32 s31, s29, s88
	s_sub_i32 s27, s27, s31
	s_ashr_i32 s26, s2, 31
	s_add_i32 s31, s29, 1
	s_sub_i32 s38, s27, s88
	v_mul_f32_e32 v0, 0x4f7ffffe, v0
	s_cmp_ge_u32 s27, s88
	v_cvt_u32_f32_e32 v0, v0
	s_cselect_b32 s29, s31, s29
	s_cselect_b32 s27, s38, s27
	s_add_i32 s31, s29, 1
	s_cmp_ge_u32 s27, s88
	s_cselect_b32 s27, s31, s29
	s_sub_i32 s31, 0, s85
	v_readfirstlane_b32 s38, v0
	s_xor_b32 s27, s27, s26
	s_mul_i32 s31, s31, s38
	s_sub_i32 s26, s27, s26
	s_mul_hi_u32 s31, s38, s31
	s_abs_i32 s29, s26
	s_add_i32 s38, s38, s31
	s_mul_hi_u32 s31, s29, s38
	s_mul_i32 s38, s31, s85
	s_sub_i32 s29, s29, s38
	s_ashr_i32 s27, s26, 31
	s_add_i32 s38, s31, 1
	s_sub_i32 s39, s29, s85
	s_cmp_ge_u32 s29, s85
	s_cselect_b32 s31, s38, s31
	s_cselect_b32 s29, s39, s29
	s_add_i32 s38, s31, 1
	s_cmp_ge_u32 s29, s85
	s_cselect_b32 s29, s38, s31
	s_xor_b32 s29, s29, s27
	s_sub_i32 s27, s29, s27
	s_add_i32 s29, s27, s89
	s_mul_i32 s27, s27, s85
	s_sub_i32 s31, s26, s27
	s_mul_i32 s26, s26, s88
	s_sub_i32 s2, s2, s26
	s_mul_i32 s2, s90, s2
	s_lshl_b32 s2, s2, 6
	s_and_b64 s[26:27], s[36:37], exec
	v_readlane_b32 s38, v254, 58
	s_cselect_b32 s77, s20, s29
	s_cselect_b32 s76, s6, s31
	s_cselect_b32 s42, 0, s2
	s_cselect_b32 s6, s93, s90
	v_readlane_b32 s39, v254, 59
	s_cmp_eq_u32 s12, 8
	s_cbranch_scc0 .Lmo_0
	s_xor_b32 s77, s77, 8
.Lmo_0:
	s_cmp_eq_u32 s12, 16
	s_cbranch_scc0 .Lfn_rm0
	s_and_b32 s26, s84, 7
	s_lshr_b32 s27, s26, 1
	s_lshl_b32 s27, s27, 5
	s_add_i32 s27, s27, 8
	s_and_b32 s77, s77, 7
	s_add_i32 s77, s77, s27
	s_and_b32 s26, s26, 1
	s_lshl_b32 s26, s26, 2
	s_and_b32 s76, s76, 3
	s_add_i32 s76, s76, s26

.LBB0_381:
	s_ashr_i32 s3, s3, 3
	s_add_i32 s3, s57, s3
	s_abs_i32 s57, s3
	s_mul_hi_u32 s70, s57, s78
	s_mul_i32 s71, s70, s2
	s_sub_i32 s57, s57, s71
	s_ashr_i32 s7, s3, 31
	s_add_i32 s71, s70, 1
	s_sub_i32 s72, s57, s2
	s_cmp_ge_u32 s57, s2
	s_cselect_b32 s70, s71, s70
	s_cselect_b32 s57, s72, s57
	s_add_i32 s71, s70, 1
	s_cmp_ge_u32 s57, s2
	s_cselect_b32 s57, s71, s70
	s_xor_b32 s57, s57, s7
	s_sub_i32 s7, s57, s7
	s_lshl_b32 s57, s7, 3
	s_sub_i32 s70, s92, s57
	s_min_i32 s70, s70, 8
	s_abs_i32 s71, s70
	v_cvt_f32_u32_e32 v0, s71
	s_sub_i32 s73, 0, s71
	s_mul_i32 s7, s7, s2
	s_sub_i32 s3, s3, s7
	v_rcp_iflag_f32_e32 v0, v0
	s_abs_i32 s7, s3
	s_xor_b32 s72, s3, s70
	s_ashr_i32 s72, s72, 31
	v_mul_f32_e32 v0, 0x4f7ffffe, v0
	v_cvt_u32_f32_e32 v0, v0
	s_nop 0
	v_readfirstlane_b32 s74, v0
	s_mul_i32 s73, s73, s74
	s_mul_hi_u32 s73, s74, s73
	s_add_i32 s74, s74, s73
	s_mul_hi_u32 s73, s7, s74
	s_mul_i32 s74, s73, s71
	s_sub_i32 s7, s7, s74
	s_add_i32 s74, s73, 1
	s_sub_i32 s75, s7, s71
	s_cmp_ge_u32 s7, s71
	s_cselect_b32 s73, s74, s73
	s_cselect_b32 s7, s75, s7
	s_add_i32 s74, s73, 1
	s_cmp_ge_u32 s7, s71
	s_cselect_b32 s7, s74, s73
	s_xor_b32 s7, s7, s72
	s_sub_i32 s7, s7, s72
	s_mul_i32 s70, s7, s70
	s_sub_i32 s3, s3, s70
	s_abs_i32 s70, s43
	s_mul_hi_u32 s71, s70, s30
	s_mul_i32 s72, s71, s88
	s_sub_i32 s70, s70, s72
	s_add_i32 s3, s3, s57
	s_ashr_i32 s57, s43, 31
	s_add_i32 s72, s71, 1
	s_sub_i32 s73, s70, s88
	s_cmp_ge_u32 s70, s88
	s_cselect_b32 s71, s72, s71
	s_cselect_b32 s70, s73, s70
	s_add_i32 s72, s71, 1
	s_cmp_ge_u32 s70, s88
	s_cselect_b32 s70, s72, s71
	s_xor_b32 s70, s70, s57
	s_sub_i32 s57, s70, s57
	s_abs_i32 s71, s57
	s_mul_hi_u32 s72, s71, s31
	s_mul_i32 s73, s72, s85
	s_sub_i32 s71, s71, s73
	s_ashr_i32 s70, s57, 31
	s_add_i32 s73, s72, 1
	s_sub_i32 s74, s71, s85
	s_cmp_ge_u32 s71, s85
	s_cselect_b32 s72, s73, s72
	s_cselect_b32 s71, s74, s71
	s_add_i32 s73, s72, 1
	s_cmp_ge_u32 s71, s85
	s_cselect_b32 s71, s73, s72
	s_xor_b32 s71, s71, s70
	s_sub_i32 s70, s71, s70
	s_add_i32 s71, s70, s89
	s_mul_i32 s70, s70, s85
	s_sub_i32 s70, s57, s70
	s_mul_i32 s57, s57, s88
	s_sub_i32 s43, s43, s57
	v_readlane_b32 s57, v252, 9
	s_mul_i32 s43, s57, s43
	s_and_b64 s[0:1], s[0:1], exec
	s_cselect_b32 s57, s3, s71
	s_cselect_b32 s7, s7, s70
	s_cselect_b32 s70, 0, s43
	s_cselect_b32 s3, s93, s90
	s_cbranch_scc0 .Lmo_1
	s_cmp_eq_u32 s12, 8
	s_cbranch_scc0 .Lmo_1
	s_xor_b32 s57, s57, 8
.Lmo_1:
	s_cmp_eq_u32 s12, 16
	s_cbranch_scc0 .Lfn_rm1
	s_and_b32 s71, s84, 7
	s_lshr_b32 s72, s71, 1
	s_lshl_b32 s72, s72, 2
	s_lshl_b32 s73, s52, 1
	s_add_i32 s73, s73, 1
	s_cmp_ge_u32 s73, 5
	s_cselect_b32 s74, 5, 0
	s_sub_i32 s73, s73, s74
	s_add_i32 s72, s72, s73
	s_lshl_b32 s72, s72, 3
	s_and_b32 s57, s57, 7
	s_add_i32 s57, s57, s72
	s_and_b32 s71, s71, 1
	s_lshl_b32 s71, s71, 2
	s_and_b32 s7, s7, 3
	s_add_i32 s7, s7, s71
